# v42 plus four individually neutral micro-changes stacked: arrival-counter polling, batched ksc loads, dead shuffle-address removal, w_in weight vector from LDS
# speedup vs baseline: 1.0027x; 1.0027x over previous
; __device__ __forceinline__ float row_part(const float* ss, int row, int fq) { const f32x4 a = ((const f32x4*)(ss + (size_t)row * 16))[fq]; return (a[0] + a[1]) + (a[2] + a[3]); }
; __device__ __forceinline__ float row_finish(float t) { t += shx(t, 16); t += shx(t, 32); return __builtin_amdgcn_rsqf(t * (1.0f / 1024.0f) + RMS_EPS); }
;     __device__ __forceinline__ void operator()(const f32x4 (&acc)[2][2][4][2], const Unit& u, int wr, int wc, int fr, int fq) const {
;         const int g = u.pn * 4 + wc;
;         int mode = 0; const float* w = mqw; float sc = 1.f, nsc = 1.f;
;         if (g >= 36) { mode = 2; w = mqw; nsc = qscale; }
;         else if (diff) { if (g < 12) { mode = 2; w = qw; nsc = qscale; } else if (g < 24) { mode = 2; w = kw; } }
;         else { if (g >= 6 && g < 12) sc = 0.125f; else if (g >= 24) mode = 1; }
;         f32x4 wv[2][2];
; #pragma unroll
;         for (int bj = 0; bj < 2; ++bj)
; #pragma unroll
;             for (int n = 0; n < 2; ++n) wv[bj][n] = *(const f32x4*)(w + 32 * bj + 8 * fq + 4 * n) * nsc;
;         const int lcol = u.pn * 256 + 64 * wc + 8 * fq;
;         float rs[2][4];
; #pragma unroll
;         for (int ai = 0; ai < 2; ++ai)
; #pragma unroll
;             for (int m = 0; m < 4; ++m) rs[ai][m] = row_part(ss, u.pm * BM + ai * HALF + wr * 64 + m * 16 + fr, fq);
; #pragma unroll
;         for (int ai = 0; ai < 2; ++ai)
; #pragma unroll
;             for (int m = 0; m < 4; ++m) rs[ai][m] = row_finish(rs[ai][m]);
.LBB0_123:
	s_lshl_b32 s9, s36, 2
	s_or_b32 s11, s9, s47
	s_cmp_gt_i32 s11, 35
	s_cselect_b64 s[34:35], -1, 0
	s_cmp_lt_i32 s11, 36
	s_cselect_b64 s[42:43], -1, 0
	s_add_i32 s11, s11, -12
	s_cmp_lt_u32 s11, -6
	s_cselect_b64 s[40:41], -1, 0
	s_sub_i32 s9, s9, 24
	s_cmp_gt_u32 s9, 11
	s_cselect_b64 s[26:27], -1, 0
	s_lshl_b32 s9, s38, 8
	v_add_u32_e32 v176, s9, v192
	v_ashrrev_i32_e32 v177, 31, v176
	v_or_b32_e32 v158, 16, v176
	v_lshlrev_b64 v[148:149], 6, v[176:177]
	v_ashrrev_i32_e32 v159, 31, v158
	v_lshl_add_u64 v[148:149], v[136:137], 0, v[148:149]
	v_lshlrev_b64 v[158:159], 6, v[158:159]
	ds_read_b128 v[150:153], v138 offset:16
	ds_read_b128 v[154:157], v138
	ds_read_b128 v[168:171], v138 offset:144
	ds_read_b128 v[178:181], v138 offset:128
	v_lshl_add_u64 v[158:159], v[136:137], 0, v[158:159]
	ds_read_b128 v[182:185], v239
	ds_read_b128 v[186:189], v239 offset:1024
	v_or_b32_e32 v148, 32, v176
	v_ashrrev_i32_e32 v149, 31, v148
	v_or_b32_e32 v158, 48, v176
	v_lshlrev_b64 v[148:149], 6, v[148:149]
	v_ashrrev_i32_e32 v159, 31, v158
	v_lshl_add_u64 v[148:149], v[136:137], 0, v[148:149]
	v_lshlrev_b64 v[158:159], 6, v[158:159]
	v_lshl_add_u64 v[158:159], v[136:137], 0, v[158:159]
	ds_read_b128 v[206:209], v239 offset:2048
	ds_read_b128 v[210:213], v239 offset:3072
	v_add_u32_e32 v174, 0x80, v176
	v_ashrrev_i32_e32 v175, 31, v174
	v_add_u32_e32 v172, 0x90, v176
	v_lshlrev_b64 v[148:149], 6, v[174:175]
	v_ashrrev_i32_e32 v173, 31, v172
	v_lshl_add_u64 v[148:149], v[136:137], 0, v[148:149]
	v_lshlrev_b64 v[158:159], 6, v[172:173]
	v_lshl_add_u64 v[158:159], v[136:137], 0, v[158:159]
	ds_read_b128 v[214:217], v239 offset:8192
	ds_read_b128 v[218:221], v239 offset:9216
	v_add_u32_e32 v166, 0xa0, v176
	v_ashrrev_i32_e32 v167, 31, v166
	v_lshlrev_b64 v[148:149], 6, v[166:167]
	v_lshl_add_u64 v[148:149], v[136:137], 0, v[148:149]
	ds_read_b128 v[222:225], v239 offset:10240
	v_add_u32_e32 v148, 0xb0, v176
	v_ashrrev_i32_e32 v149, 31, v148
	v_lshlrev_b64 v[158:159], 6, v[148:149]
	v_lshl_add_u64 v[158:159], v[136:137], 0, v[158:159]
	ds_read_b128 v[226:229], v239 offset:11264
	s_nop 0
	v_mov_b32_e32 v158, v201
	v_cndmask_b32_e64 v190, v203, 1.0, s[42:43]
	v_lshlrev_b32_e32 v158, 2, v158
	v_xor_b32_e32 v173, 0x80, v158
	s_nop 2
	s_mov_b64 s[38:39], -1
	s_nop 1
	s_and_b64 vcc, exec, s[42:43]
	s_waitcnt lgkmcnt(0)
	v_pk_mul_f32 v[158:159], v[190:191], v[152:153] op_sel_hi:[0,1]
	v_pk_mul_f32 v[160:161], v[190:191], v[150:151] op_sel_hi:[0,1]
	v_pk_mul_f32 v[152:153], v[190:191], v[168:169] op_sel_hi:[0,1]
	v_pk_mul_f32 v[150:151], v[190:191], v[170:171] op_sel_hi:[0,1]
	v_mov_b32_e32 v168, v183
	v_mov_b32_e32 v169, v184
	v_mov_b32_e32 v183, v185
	v_pk_add_f32 v[168:169], v[168:169], v[182:183]
	v_add_f32_e32 v170, v186, v187
	v_add_f32_e32 v168, v168, v169
	v_mov_b32_e32 v149, v168
	s_nop 1
	v_permlane16_swap_b32_e32 v149, v168
	v_add_f32_e32 v171, v188, v189
	v_add_f32_e32 v169, v170, v171
	v_mov_b32_e32 v167, v169
	s_nop 1
	v_permlane16_swap_b32_e32 v167, v169
	v_pk_mul_f32 v[162:163], v[190:191], v[156:157] op_sel_hi:[0,1]
	s_waitcnt lgkmcnt(0)
	v_add_f32_e32 v149, v168, v149
	v_mov_b32_e32 v168, v149
	s_nop 1
	v_permlane32_swap_b32_e32 v168, v149
	v_pk_mul_f32 v[156:157], v[190:191], v[178:179] op_sel_hi:[0,1]
	v_add_f32_e32 v179, v212, v213
	s_waitcnt lgkmcnt(0)
	v_add_f32_e32 v212, v169, v167
	v_add_f32_e32 v175, v206, v207
	s_waitcnt lgkmcnt(0)
	v_add_f32_e32 v149, v149, v168
	v_fmamk_f32 v149, v149, 0x3a800000, v202
	v_rsq_f32_e32 v168, v149
	s_nop 0
	v_add_f32_e32 v177, v208, v209
	s_nop 1
	v_mov_b32_e32 v213, v212
	s_nop 1
	v_permlane32_swap_b32_e32 v213, v212
	s_nop 0
	v_add_f32_e32 v170, v175, v177
	s_nop 1
	v_mov_b32_e32 v149, v170
	s_nop 1
	v_permlane16_swap_b32_e32 v149, v170
	v_mov_b32_e32 v167, v201
	s_nop 0
	v_add_f32_e32 v178, v210, v211
	s_nop 0
	v_add_f32_e32 v171, v178, v179
	s_nop 0
	v_mov_b32_e32 v169, v171
	s_nop 1
	v_permlane16_swap_b32_e32 v169, v171
	s_waitcnt lgkmcnt(0)
	v_add_f32_e32 v210, v170, v149
	v_lshlrev_b32_e32 v149, 2, v167
	v_xor_b32_e32 v149, 0x80, v149
	v_mov_b32_e32 v211, v210
	s_nop 1
	v_permlane32_swap_b32_e32 v211, v210
	s_nop 0
	s_waitcnt lgkmcnt(0)
	v_add_f32_e32 v208, v171, v169
	s_nop 1
	v_mov_b32_e32 v209, v208
	s_nop 1
	v_permlane32_swap_b32_e32 v209, v208
	s_nop 0
	v_pk_mul_f32 v[164:165], v[190:191], v[154:155] op_sel_hi:[0,1]
	v_pk_mul_f32 v[154:155], v[190:191], v[180:181] op_sel_hi:[0,1]
	v_add_f32_e32 v180, v214, v215
	v_add_f32_e32 v181, v216, v217
	s_nop 0
	v_add_f32_e32 v175, v180, v181
	s_nop 0
	v_mov_b32_e32 v149, v175
	s_nop 1
	v_permlane16_swap_b32_e32 v149, v175
	v_mov_b32_e32 v167, v201
	s_nop 0
	v_add_f32_e32 v182, v218, v219
	v_add_f32_e32 v183, v220, v221
	s_nop 0
	v_add_f32_e32 v177, v182, v183
	s_nop 0
	v_mov_b32_e32 v169, v177
	s_nop 1
	v_permlane16_swap_b32_e32 v169, v177
	s_waitcnt lgkmcnt(0)
	v_add_f32_e32 v206, v175, v149
	v_lshlrev_b32_e32 v149, 2, v167
	v_xor_b32_e32 v149, 0x80, v149
	v_mov_b32_e32 v207, v206
	s_nop 1
	v_permlane32_swap_b32_e32 v207, v206
	s_nop 0
	s_waitcnt lgkmcnt(0)
	v_add_f32_e32 v177, v177, v169
	s_nop 1
	v_mov_b32_e32 v205, v177
	s_nop 1
	v_permlane32_swap_b32_e32 v205, v177
	s_nop 0
	v_add_f32_e32 v184, v222, v223
	v_add_f32_e32 v185, v224, v225
	s_nop 0
	v_add_f32_e32 v178, v184, v185
	s_nop 0
	v_mov_b32_e32 v167, v201
	s_nop 0
	v_mov_b32_e32 v149, v178
	s_nop 1
	v_permlane16_swap_b32_e32 v149, v178
	v_add_f32_e32 v186, v226, v227
	v_add_f32_e32 v187, v228, v229
	s_nop 0
	v_add_f32_e32 v179, v186, v187
	s_nop 0
	v_mov_b32_e32 v169, v179
	s_nop 1
	v_permlane16_swap_b32_e32 v169, v179
	s_waitcnt lgkmcnt(0)
	v_add_f32_e32 v173, v178, v149
	v_lshlrev_b32_e32 v149, 2, v167
	s_nop 0
	v_xor_b32_e32 v149, 0x80, v149
	s_nop 0
	v_mov_b32_e32 v175, v173
	s_nop 1
	v_permlane32_swap_b32_e32 v175, v173
	s_waitcnt lgkmcnt(0)
	v_add_f32_e32 v149, v179, v169
	s_nop 0
	v_mov_b32_e32 v167, v149
	s_nop 1
	v_permlane32_swap_b32_e32 v167, v149
	v_pk_mul_f32 v[190:191], v[126:127], v[168:169] op_sel_hi:[1,0]
	v_pk_mul_f32 v[184:185], v[124:125], v[168:169] op_sel_hi:[1,0]
	v_pk_mul_f32 v[186:187], v[122:123], v[168:169] op_sel_hi:[1,0]
	v_pk_mul_f32 v[188:189], v[120:121], v[168:169] op_sel_hi:[1,0]
	v_pk_mul_f32 v[180:181], v[118:119], v[168:169] op_sel_hi:[1,0]
	v_pk_mul_f32 v[182:183], v[116:117], v[168:169] op_sel_hi:[1,0]
	v_pk_mul_f32 v[178:179], v[114:115], v[168:169] op_sel_hi:[1,0]
	v_pk_mul_f32 v[170:171], v[112:113], v[168:169] op_sel_hi:[1,0]
	s_cbranch_vccnz .LBB0_125
; __device__ __forceinline__ float sq4(f32x4 v) { return (v[0] * v[0] + v[1] * v[1]) + (v[2] * v[2] + v[3] * v[3]); }
;     __device__ __forceinline__ void operator()(const f32x4 (&acc)[2][2][4][2], const Unit& u, int wr, int wc, int fr, int fq) const {
;     ...
;                 if (mode == 2) {
;                     float q = (sq4(v[0][0]) + sq4(v[0][1])) + (sq4(v[1][0]) + sq4(v[1][1]));
;                     q += shx(q, 16); q += shx(q, 32);
;                     const float r2 = __builtin_amdgcn_rsqf(q * (1.0f / 64.0f) + RMS_EPS);
; #pragma unroll
;                     for (int bj = 0; bj < 2; ++bj)
; #pragma unroll
;                         for (int n = 0; n < 2; ++n) v[bj][n] = v[bj][n] * r2 * wv[bj][n];
	v_mov_b32_e32 v114, v185
	v_mov_b32_e32 v115, v183
	v_mov_b32_e32 v112, v184
	v_mov_b32_e32 v113, v182
	v_pk_mul_f32 v[114:115], v[114:115], v[114:115]
	v_mov_b32_e32 v116, v191
	v_mov_b32_e32 v117, v181
	v_pk_fma_f32 v[112:113], v[112:113], v[112:113], v[114:115]
	v_mov_b32_e32 v114, v190
	v_mov_b32_e32 v115, v180
	v_pk_mul_f32 v[116:117], v[116:117], v[116:117]
	v_mov_b32_e32 v118, v187
	v_pk_fma_f32 v[114:115], v[114:115], v[114:115], v[116:117]
	v_mov_b32_e32 v116, v189
	v_mov_b32_e32 v117, v171
	v_pk_add_f32 v[112:113], v[112:113], v[114:115]
	v_mov_b32_e32 v114, v188
	v_mov_b32_e32 v115, v170
	v_pk_mul_f32 v[116:117], v[116:117], v[116:117]
	v_mov_b32_e32 v119, v179
	v_pk_fma_f32 v[114:115], v[114:115], v[114:115], v[116:117]
	v_mov_b32_e32 v116, v186
	v_mov_b32_e32 v117, v178
	v_pk_mul_f32 v[118:119], v[118:119], v[118:119]
	s_mov_b64 s[38:39], 0
	v_pk_fma_f32 v[116:117], v[116:117], v[116:117], v[118:119]
	s_nop 0
	v_pk_add_f32 v[114:115], v[114:115], v[116:117]
	s_nop 0
	v_pk_add_f32 v[112:113], v[112:113], v[114:115]
	s_nop 0
	v_add_f32_e32 v112, v112, v113
	s_nop 0
	s_nop 0
	s_nop 1
	v_mov_b32_e32 v113, v112
	s_nop 1
	v_permlane16_swap_b32_e32 v113, v112
	s_waitcnt lgkmcnt(0)
	v_add_f32_e32 v112, v112, v113
	s_nop 0
	s_nop 0
	s_nop 1
	v_mov_b32_e32 v113, v112
	s_nop 1
	v_permlane32_swap_b32_e32 v113, v112
	s_waitcnt lgkmcnt(0)
	v_add_f32_e32 v112, v112, v113
	v_fmamk_f32 v112, v112, 0x3c800000, v202
	v_rsq_f32_e32 v124, v112
	s_nop 0
	v_pk_mul_f32 v[112:113], v[184:185], v[124:125] op_sel_hi:[1,0]
	v_pk_mul_f32 v[114:115], v[190:191], v[124:125] op_sel_hi:[1,0]
	v_pk_mul_f32 v[116:117], v[188:189], v[124:125] op_sel_hi:[1,0]
	v_pk_mul_f32 v[118:119], v[186:187], v[124:125] op_sel_hi:[1,0]
	v_pk_mul_f32 v[120:121], v[182:183], v[124:125] op_sel_hi:[1,0]
	v_pk_mul_f32 v[122:123], v[180:181], v[124:125] op_sel_hi:[1,0]
	v_pk_mul_f32 v[168:169], v[170:171], v[124:125] op_sel_hi:[1,0]
	v_pk_mul_f32 v[124:125], v[178:179], v[124:125] op_sel_hi:[1,0]
	v_pk_mul_f32 v[114:115], v[162:163], v[114:115]
	v_pk_mul_f32 v[112:113], v[164:165], v[112:113]
	v_pk_mul_f32 v[118:119], v[158:159], v[118:119]
	v_pk_mul_f32 v[116:117], v[160:161], v[116:117]
	v_pk_mul_f32 v[122:123], v[154:155], v[122:123]
	v_pk_mul_f32 v[120:121], v[156:157], v[120:121]
	v_pk_mul_f32 v[126:127], v[150:151], v[124:125]
	v_pk_mul_f32 v[124:125], v[152:153], v[168:169]

; __device__ __forceinline__ float row_part(const float* ss, int row, int fq) { const f32x4 a = ((const f32x4*)(ss + (size_t)row * 16))[fq]; return (a[0] + a[1]) + (a[2] + a[3]); }
; __device__ __forceinline__ float row_finish(float t) { t += shx(t, 16); t += shx(t, 32); return __builtin_amdgcn_rsqf(t * (1.0f / 1024.0f) + RMS_EPS); }
;     __device__ __forceinline__ void operator()(const f32x4 (&acc)[2][2][4][2], const Unit& u, int wr, int wc, int fr, int fq) const {
;         const int g = u.pn * 4 + wc;
;         int mode = 0; const float* w = mqw; float sc = 1.f, nsc = 1.f;
;         if (g >= 36) { mode = 2; w = mqw; nsc = qscale; }
;         else if (diff) { if (g < 12) { mode = 2; w = qw; nsc = qscale; } else if (g < 24) { mode = 2; w = kw; } }
;         else { if (g >= 6 && g < 12) sc = 0.125f; else if (g >= 24) mode = 1; }
;         f32x4 wv[2][2];
; #pragma unroll
;         for (int bj = 0; bj < 2; ++bj)
; #pragma unroll
;             for (int n = 0; n < 2; ++n) wv[bj][n] = *(const f32x4*)(w + 32 * bj + 8 * fq + 4 * n) * nsc;
;         const int lcol = u.pn * 256 + 64 * wc + 8 * fq;
;         float rs[2][4];
; #pragma unroll
;         for (int ai = 0; ai < 2; ++ai)
; #pragma unroll
;             for (int m = 0; m < 4; ++m) rs[ai][m] = row_part(ss, u.pm * BM + ai * HALF + wr * 64 + m * 16 + fr, fq);
; #pragma unroll
;         for (int ai = 0; ai < 2; ++ai)
; #pragma unroll
;             for (int m = 0; m < 4; ++m) rs[ai][m] = row_finish(rs[ai][m]);
.LBB0_1191:
	ds_read_b128 v[148:151], v138 offset:16
	ds_read_b128 v[152:155], v138
	ds_read_b128 v[166:169], v138 offset:144
	ds_read_b128 v[170:173], v138 offset:128
	s_lshl_b32 s0, s50, 2
	s_or_b32 s4, s0, s67
	s_cmp_gt_i32 s4, 35
	s_cselect_b64 s[48:49], -1, 0
	s_cmp_lt_i32 s4, 36
	s_cselect_b64 s[56:57], -1, 0
	s_add_i32 s4, s4, -12
	s_cmp_lt_u32 s4, -6
	s_cselect_b64 s[54:55], -1, 0
	s_sub_i32 s0, s0, 24
	s_cmp_gt_u32 s0, 11
	s_cselect_b64 s[46:47], -1, 0
	s_lshl_b32 s0, s52, 8
	v_add_u32_e32 v176, s0, v192
	v_cndmask_b32_e64 v158, v203, 1.0, s[56:57]
	v_ashrrev_i32_e32 v177, 31, v176
	v_add_u32_e32 v174, 0x80, v176
	v_ashrrev_i32_e32 v175, 31, v174
	s_mov_b64 s[52:53], -1
	s_and_b64 vcc, exec, s[56:57]
	s_waitcnt lgkmcnt(0)
	v_pk_mul_f32 v[150:151], v[158:159], v[150:151] op_sel_hi:[0,1]
	v_pk_mul_f32 v[160:161], v[158:159], v[152:153] op_sel_hi:[0,1]
	v_pk_mul_f32 v[152:153], v[158:159], v[148:149] op_sel_hi:[0,1]
	v_lshlrev_b64 v[148:149], 6, v[176:177]
	v_lshl_add_u64 v[148:149], v[136:137], 0, v[148:149]
	v_pk_mul_f32 v[156:157], v[158:159], v[154:155] op_sel_hi:[0,1]
	v_pk_mul_f32 v[162:163], v[158:159], v[172:173] op_sel_hi:[0,1]
	v_pk_mul_f32 v[164:165], v[158:159], v[170:171] op_sel_hi:[0,1]
	v_pk_mul_f32 v[154:155], v[158:159], v[168:169] op_sel_hi:[0,1]
	v_pk_mul_f32 v[158:159], v[158:159], v[166:167] op_sel_hi:[0,1]
	ds_read_b128 v[166:169], v239
	v_add_u32_e32 v172, 0x90, v176
	v_ashrrev_i32_e32 v173, 31, v172
	s_waitcnt lgkmcnt(0)
	v_mov_b32_e32 v148, v167
	v_mov_b32_e32 v149, v168
	v_mov_b32_e32 v167, v169
	v_pk_add_f32 v[148:149], v[148:149], v[166:167]
	s_nop 0
	v_add_f32_e32 v177, v148, v149
	v_or_b32_e32 v148, 16, v176
	v_ashrrev_i32_e32 v149, 31, v148
	v_lshlrev_b64 v[148:149], 6, v[148:149]
	v_lshl_add_u64 v[148:149], v[136:137], 0, v[148:149]
	ds_read_b128 v[166:169], v239 offset:1024
	s_waitcnt lgkmcnt(0)
	v_add_f32_e32 v148, v166, v167
	v_add_f32_e32 v149, v168, v169
	v_add_f32_e32 v178, v148, v149
	v_or_b32_e32 v148, 32, v176
	v_ashrrev_i32_e32 v149, 31, v148
	v_lshlrev_b64 v[148:149], 6, v[148:149]
	v_lshl_add_u64 v[148:149], v[136:137], 0, v[148:149]
	ds_read_b128 v[166:169], v239 offset:2048
	s_waitcnt lgkmcnt(0)
	v_add_f32_e32 v148, v166, v167
	v_add_f32_e32 v149, v168, v169
	v_add_f32_e32 v179, v148, v149
	v_or_b32_e32 v148, 48, v176
	v_ashrrev_i32_e32 v149, 31, v148
	v_lshlrev_b64 v[148:149], 6, v[148:149]
	v_lshl_add_u64 v[148:149], v[136:137], 0, v[148:149]
	ds_read_b128 v[166:169], v239 offset:3072
	s_waitcnt lgkmcnt(0)
	v_add_f32_e32 v148, v166, v167
	v_add_f32_e32 v149, v168, v169
	v_add_f32_e32 v180, v148, v149
	v_lshlrev_b64 v[148:149], 6, v[174:175]
	v_lshl_add_u64 v[148:149], v[136:137], 0, v[148:149]
	ds_read_b128 v[166:169], v239 offset:8192
	s_waitcnt lgkmcnt(0)
	v_add_f32_e32 v148, v166, v167
	v_add_f32_e32 v149, v168, v169
	v_add_f32_e32 v175, v148, v149
	v_lshlrev_b64 v[148:149], 6, v[172:173]
	v_lshl_add_u64 v[148:149], v[136:137], 0, v[148:149]
	ds_read_b128 v[166:169], v239 offset:9216
	s_waitcnt lgkmcnt(0)
	v_add_f32_e32 v148, v166, v167
	v_add_u32_e32 v166, 0xa0, v176
	v_add_f32_e32 v149, v168, v169
	v_ashrrev_i32_e32 v167, 31, v166
	v_add_f32_e32 v173, v148, v149
	v_lshlrev_b64 v[148:149], 6, v[166:167]
	v_lshl_add_u64 v[148:149], v[136:137], 0, v[148:149]
	ds_read_b128 v[168:171], v239 offset:10240
	s_waitcnt lgkmcnt(0)
	v_add_f32_e32 v148, v168, v169
	v_add_f32_e32 v149, v170, v171
	v_add_f32_e32 v167, v148, v149
	v_add_u32_e32 v148, 0xb0, v176
	v_ashrrev_i32_e32 v149, 31, v148
	v_lshlrev_b64 v[168:169], 6, v[148:149]
	v_lshl_add_u64 v[168:169], v[136:137], 0, v[168:169]
	ds_read_b128 v[168:171], v239 offset:11264
	s_waitcnt lgkmcnt(0)
	v_add_f32_e32 v149, v168, v169
	v_add_f32_e32 v168, v170, v171
	v_add_f32_e32 v149, v149, v168
	s_nop 0
	s_nop 2
	v_mov_b32_e32 v168, v177
	s_nop 1
	v_permlane16_swap_b32_e32 v168, v177
	s_waitcnt lgkmcnt(0)
	v_add_f32_e32 v168, v177, v168
	s_nop 1
	v_mov_b32_e32 v169, v168
	s_nop 1
	v_permlane32_swap_b32_e32 v169, v168
	s_waitcnt lgkmcnt(0)
	v_add_f32_e32 v168, v168, v169
	s_nop 0
	v_fmamk_f32 v168, v168, 0x3a800000, v202
	s_nop 1
	v_mov_b32_e32 v169, v178
	s_nop 1
	v_permlane16_swap_b32_e32 v169, v178
	v_rsq_f32_e32 v168, v168
	s_waitcnt lgkmcnt(0)
	v_add_f32_e32 v212, v178, v169
	s_nop 0
	s_nop 0
	s_nop 1
	v_mov_b32_e32 v213, v212
	s_nop 1
	v_permlane32_swap_b32_e32 v213, v212
	s_nop 0
	s_nop 0
	s_nop 1
	v_mov_b32_e32 v169, v179
	s_nop 1
	v_permlane16_swap_b32_e32 v169, v179
	s_waitcnt lgkmcnt(0)
	v_add_f32_e32 v210, v179, v169
	s_nop 0
	s_nop 0
	s_nop 1
	v_mov_b32_e32 v211, v210
	s_nop 1
	v_permlane32_swap_b32_e32 v211, v210
	s_nop 0
	s_nop 0
	s_nop 1
	v_mov_b32_e32 v169, v180
	s_nop 1
	v_permlane16_swap_b32_e32 v169, v180
	s_waitcnt lgkmcnt(0)
	v_add_f32_e32 v208, v180, v169
	s_nop 0
	s_nop 0
	s_nop 1
	v_mov_b32_e32 v209, v208
	s_nop 1
	v_permlane32_swap_b32_e32 v209, v208
	s_nop 0
	s_nop 0
	s_nop 1
	v_mov_b32_e32 v169, v175
	s_nop 1
	v_permlane16_swap_b32_e32 v169, v175
	s_waitcnt lgkmcnt(0)
	v_add_f32_e32 v206, v175, v169
	s_nop 0
	s_nop 0
	s_nop 1
	v_mov_b32_e32 v207, v206
	s_nop 1
	v_permlane32_swap_b32_e32 v207, v206
	s_nop 0
	s_nop 0
	s_nop 1
	v_mov_b32_e32 v169, v173
	s_nop 1
	v_permlane16_swap_b32_e32 v169, v173
	s_waitcnt lgkmcnt(0)
	v_add_f32_e32 v177, v173, v169
	s_nop 0
	s_nop 0
	s_nop 1
	v_mov_b32_e32 v205, v177
	s_nop 1
	v_permlane32_swap_b32_e32 v205, v177
	s_nop 0
	s_nop 0
	s_nop 1
	v_mov_b32_e32 v169, v167
	s_nop 1
	v_permlane16_swap_b32_e32 v169, v167
	s_waitcnt lgkmcnt(0)
	v_add_f32_e32 v173, v167, v169
	s_nop 0
	v_pk_mul_f32 v[188:189], v[126:127], v[168:169] op_sel_hi:[1,0]
	s_nop 1
	v_mov_b32_e32 v175, v173
	s_nop 1
	v_permlane32_swap_b32_e32 v175, v173
	s_nop 0
	v_pk_mul_f32 v[190:191], v[124:125], v[168:169] op_sel_hi:[1,0]
	s_nop 1
	v_mov_b32_e32 v167, v149
	s_nop 1
	v_permlane16_swap_b32_e32 v167, v149
	v_pk_mul_f32 v[184:185], v[122:123], v[168:169] op_sel_hi:[1,0]
	v_pk_mul_f32 v[186:187], v[120:121], v[168:169] op_sel_hi:[1,0]
	v_pk_mul_f32 v[180:181], v[118:119], v[168:169] op_sel_hi:[1,0]
	v_pk_mul_f32 v[182:183], v[116:117], v[168:169] op_sel_hi:[1,0]
	s_waitcnt lgkmcnt(0)
	v_add_f32_e32 v149, v149, v167
	s_nop 0
	v_pk_mul_f32 v[178:179], v[114:115], v[168:169] op_sel_hi:[1,0]
	s_nop 1
	v_mov_b32_e32 v167, v149
	s_nop 1
	v_permlane32_swap_b32_e32 v167, v149
	v_pk_mul_f32 v[170:171], v[112:113], v[168:169] op_sel_hi:[1,0]
	s_cbranch_vccnz .LBB0_1193
; __device__ __forceinline__ float sq4(f32x4 v) { return (v[0] * v[0] + v[1] * v[1]) + (v[2] * v[2] + v[3] * v[3]); }
;     __device__ __forceinline__ void operator()(const f32x4 (&acc)[2][2][4][2], const Unit& u, int wr, int wc, int fr, int fq) const {
;     ...
;                 if (mode == 2) {
;                     float q = (sq4(v[0][0]) + sq4(v[0][1])) + (sq4(v[1][0]) + sq4(v[1][1]));
;                     q += shx(q, 16); q += shx(q, 32);
;                     const float r2 = __builtin_amdgcn_rsqf(q * (1.0f / 64.0f) + RMS_EPS);
; #pragma unroll
;                     for (int bj = 0; bj < 2; ++bj)
; #pragma unroll
;                         for (int n = 0; n < 2; ++n) v[bj][n] = v[bj][n] * r2 * wv[bj][n];
	v_mov_b32_e32 v114, v191
	v_mov_b32_e32 v115, v183
	v_mov_b32_e32 v112, v190
	v_mov_b32_e32 v113, v182
	v_pk_mul_f32 v[114:115], v[114:115], v[114:115]
	v_mov_b32_e32 v116, v189
	v_mov_b32_e32 v117, v181
	v_pk_fma_f32 v[112:113], v[112:113], v[112:113], v[114:115]
	v_mov_b32_e32 v114, v188
	v_mov_b32_e32 v115, v180
	v_pk_mul_f32 v[116:117], v[116:117], v[116:117]
	v_mov_b32_e32 v118, v185
	v_pk_fma_f32 v[114:115], v[114:115], v[114:115], v[116:117]
	v_mov_b32_e32 v116, v187
	v_mov_b32_e32 v117, v171
	v_pk_add_f32 v[112:113], v[112:113], v[114:115]
	v_mov_b32_e32 v114, v186
	v_mov_b32_e32 v115, v170
	v_pk_mul_f32 v[116:117], v[116:117], v[116:117]
	v_mov_b32_e32 v119, v179
	v_pk_fma_f32 v[114:115], v[114:115], v[114:115], v[116:117]
	v_mov_b32_e32 v116, v184
	v_mov_b32_e32 v117, v178
	v_pk_mul_f32 v[118:119], v[118:119], v[118:119]
	s_mov_b64 s[52:53], 0
	v_pk_fma_f32 v[116:117], v[116:117], v[116:117], v[118:119]
	s_nop 0
	v_pk_add_f32 v[114:115], v[114:115], v[116:117]
	s_nop 0
	v_pk_add_f32 v[112:113], v[112:113], v[114:115]
	s_nop 0
	v_add_f32_e32 v112, v112, v113
	s_nop 0
	s_nop 0
	s_nop 1
	v_mov_b32_e32 v113, v112
	s_nop 1
	v_permlane16_swap_b32_e32 v113, v112
	s_waitcnt lgkmcnt(0)
	v_add_f32_e32 v112, v112, v113
	s_nop 0
	s_nop 0
	s_nop 1
	v_mov_b32_e32 v113, v112
	s_nop 1
	v_permlane32_swap_b32_e32 v113, v112
	s_waitcnt lgkmcnt(0)
	v_add_f32_e32 v112, v112, v113
	v_fmamk_f32 v112, v112, 0x3c800000, v202
	v_rsq_f32_e32 v124, v112
	s_nop 0
	v_pk_mul_f32 v[112:113], v[190:191], v[124:125] op_sel_hi:[1,0]
	v_pk_mul_f32 v[114:115], v[188:189], v[124:125] op_sel_hi:[1,0]
	v_pk_mul_f32 v[116:117], v[186:187], v[124:125] op_sel_hi:[1,0]
	v_pk_mul_f32 v[118:119], v[184:185], v[124:125] op_sel_hi:[1,0]
	v_pk_mul_f32 v[120:121], v[182:183], v[124:125] op_sel_hi:[1,0]
	v_pk_mul_f32 v[122:123], v[180:181], v[124:125] op_sel_hi:[1,0]
	v_pk_mul_f32 v[168:169], v[170:171], v[124:125] op_sel_hi:[1,0]
	v_pk_mul_f32 v[124:125], v[178:179], v[124:125] op_sel_hi:[1,0]
	v_pk_mul_f32 v[114:115], v[156:157], v[114:115]
	v_pk_mul_f32 v[112:113], v[160:161], v[112:113]
	v_pk_mul_f32 v[118:119], v[150:151], v[118:119]
	v_pk_mul_f32 v[116:117], v[152:153], v[116:117]
	v_pk_mul_f32 v[122:123], v[162:163], v[122:123]
	v_pk_mul_f32 v[120:121], v[164:165], v[120:121]
	v_pk_mul_f32 v[126:127], v[154:155], v[124:125]
	v_pk_mul_f32 v[124:125], v[158:159], v[168:169]
